# v39 + P0 weight conversion of the plain matrices through a hand-written loop with 3 tiles of f32 rows in flight per wave
# speedup vs baseline: 1.0036x; 1.0001x over previous
.LBB0_24:
	s_cmpk_lt_i32 s89, 0x280
	s_cbranch_scc1 .Lwf_generic
	s_cmpk_ge_i32 s89, 0x1680
	s_cbranch_scc1 .Lwf_generic
	s_cmpk_lg_u32 s61, 0x16e0
	s_cbranch_scc1 .Lwf_generic
	v_and_b32_e32 v29, 63, v155
	v_lshrrev_b32_e32 v24, 6, v155
	v_lshlrev_b32_e32 v26, 2, v29
	v_lshlrev_b32_e32 v29, 1, v29
	v_readfirstlane_b32 s58, v24
	s_load_dword s6, s[0:1], 0x4c8
	s_waitcnt lgkmcnt(0)
	s_lshl_b32 s58, s58, 4
	s_add_i32 s7, s89, 0xfffffe80
	s_mov_b32 s30, 2
	s_cmpk_ge_i32 s7, 0x300
	s_cselect_b32 s30, 3, s30
	s_cmpk_ge_i32 s7, 0x500
	s_cselect_b32 s30, 4, s30
	s_cmpk_ge_i32 s7, 0x700
	s_cselect_b32 s30, 5, s30
	s_cmpk_ge_i32 s7, 0x900
	s_cselect_b32 s30, 6, s30
	s_cmpk_ge_i32 s7, 0xb00
	s_cselect_b32 s30, 7, s30
	s_cmpk_ge_i32 s7, 0xd00
	s_cselect_b32 s30, 8, s30
	s_cmpk_ge_i32 s7, 0xf00
	s_cselect_b32 s30, 9, s30
	s_cmpk_ge_i32 s7, 0x1100
	s_cselect_b32 s30, 10, s30
	s_cmpk_ge_i32 s7, 0x1280
	s_cselect_b32 s30, 11, s30
	s_cmpk_ge_i32 s7, 0x1400
	s_cselect_b32 s30, 12, s30
	s_cmpk_ge_i32 s7, 0x1480
	s_cselect_b32 s30, 13, s30
	s_mul_i32 s59, s30, 48
	s_add_u32 s10, s0, s59
	s_addc_u32 s11, s1, 0
	s_load_dwordx2 s[50:51], s[10:11], 0x100
	s_load_dwordx2 s[52:53], s[10:11], 0x110
	s_load_dwordx2 s[90:91], s[10:11], 0x118
	s_load_dword s30, s[10:11], 0x128
	s_load_dwordx2 vcc, s[0:1], 0xf8
	s_waitcnt lgkmcnt(0)
	s_sub_i32 s7, s7, s30
	s_lshr_b32 s59, s90, 7
	s_add_i32 s10, s59, -1
	s_and_b32 s10, s7, s10
	s_ff1_i32_b32 s59, s59
	s_lshr_b32 s7, s7, s59
	s_lshl_b32 s10, s10, 7
	s_add_i32 s10, s10, s58
	s_lshl_b32 s11, s7, 6
	s_mul_i32 s59, s10, s91
	s_add_i32 s59, s59, s11
	s_lshl_b32 s59, s59, 2
	s_add_u32 s50, s50, s59
	s_addc_u32 s51, s51, 0
	s_mul_i32 s59, s11, s90
	s_add_i32 s59, s59, s10
	s_lshl_b32 s59, s59, 1
	s_add_u32 s52, s52, s59
	s_addc_u32 s53, s53, 0
	s_add_u32 s52, s52, vcc_lo
	s_addc_u32 s53, s53, vcc_hi
	v_mul_u32_u24_e32 v27, s90, v29
	s_lshl_b32 s91, s91, 2
	global_load_dword v0, v26, s[50:51] nt
	s_add_u32 s50, s50, s91
	s_addc_u32 s51, s51, 0
	global_load_dword v1, v26, s[50:51] nt
	s_add_u32 s50, s50, s91
	s_addc_u32 s51, s51, 0
	global_load_dword v2, v26, s[50:51] nt
	s_add_u32 s50, s50, s91
	s_addc_u32 s51, s51, 0
	global_load_dword v3, v26, s[50:51] nt
	s_add_u32 s50, s50, s91
	s_addc_u32 s51, s51, 0
	global_load_dword v4, v26, s[50:51] nt
	s_add_u32 s50, s50, s91
	s_addc_u32 s51, s51, 0
	global_load_dword v5, v26, s[50:51] nt
	s_add_u32 s50, s50, s91
	s_addc_u32 s51, s51, 0
	global_load_dword v6, v26, s[50:51] nt
	s_add_u32 s50, s50, s91
	s_addc_u32 s51, s51, 0
	global_load_dword v7, v26, s[50:51] nt
	s_add_u32 s50, s50, s91
	s_addc_u32 s51, s51, 0
	global_load_dword v8, v26, s[50:51] nt
	s_add_u32 s50, s50, s91
	s_addc_u32 s51, s51, 0
	global_load_dword v9, v26, s[50:51] nt
	s_add_u32 s50, s50, s91
	s_addc_u32 s51, s51, 0
	global_load_dword v10, v26, s[50:51] nt
	s_add_u32 s50, s50, s91
	s_addc_u32 s51, s51, 0
	global_load_dword v11, v26, s[50:51] nt
	s_add_u32 s50, s50, s91
	s_addc_u32 s51, s51, 0
	global_load_dword v12, v26, s[50:51] nt
	s_add_u32 s50, s50, s91
	s_addc_u32 s51, s51, 0
	global_load_dword v13, v26, s[50:51] nt
	s_add_u32 s50, s50, s91
	s_addc_u32 s51, s51, 0
	global_load_dword v14, v26, s[50:51] nt
	s_add_u32 s50, s50, s91
	s_addc_u32 s51, s51, 0
	global_load_dword v15, v26, s[50:51] nt
	s_add_i32 s89, s89, s6
	s_cmpk_ge_i32 s89, 0x1680
	s_cbranch_scc1 .Lwf_pdrain1
	s_add_i32 s7, s89, 0xfffffe80
	s_mov_b32 s30, 2
	s_cmpk_ge_i32 s7, 0x300
	s_cselect_b32 s30, 3, s30
	s_cmpk_ge_i32 s7, 0x500
	s_cselect_b32 s30, 4, s30
	s_cmpk_ge_i32 s7, 0x700
	s_cselect_b32 s30, 5, s30
	s_cmpk_ge_i32 s7, 0x900
	s_cselect_b32 s30, 6, s30
	s_cmpk_ge_i32 s7, 0xb00
	s_cselect_b32 s30, 7, s30
	s_cmpk_ge_i32 s7, 0xd00
	s_cselect_b32 s30, 8, s30
	s_cmpk_ge_i32 s7, 0xf00
	s_cselect_b32 s30, 9, s30
	s_cmpk_ge_i32 s7, 0x1100
	s_cselect_b32 s30, 10, s30
	s_cmpk_ge_i32 s7, 0x1280
	s_cselect_b32 s30, 11, s30
	s_cmpk_ge_i32 s7, 0x1400
	s_cselect_b32 s30, 12, s30
	s_cmpk_ge_i32 s7, 0x1480
	s_cselect_b32 s30, 13, s30
	s_mul_i32 s59, s30, 48
	s_add_u32 s10, s0, s59
	s_addc_u32 s11, s1, 0
	s_load_dwordx2 s[50:51], s[10:11], 0x100
	s_load_dwordx2 s[54:55], s[10:11], 0x110
	s_load_dwordx2 s[90:91], s[10:11], 0x118
	s_load_dword s30, s[10:11], 0x128
	s_load_dwordx2 vcc, s[0:1], 0xf8
	s_waitcnt lgkmcnt(0)
	s_sub_i32 s7, s7, s30
	s_lshr_b32 s59, s90, 7
	s_add_i32 s10, s59, -1
	s_and_b32 s10, s7, s10
	s_ff1_i32_b32 s59, s59
	s_lshr_b32 s7, s7, s59
	s_lshl_b32 s10, s10, 7
	s_add_i32 s10, s10, s58
	s_lshl_b32 s11, s7, 6
	s_mul_i32 s59, s10, s91
	s_add_i32 s59, s59, s11
	s_lshl_b32 s59, s59, 2
	s_add_u32 s50, s50, s59
	s_addc_u32 s51, s51, 0
	s_mul_i32 s59, s11, s90
	s_add_i32 s59, s59, s10
	s_lshl_b32 s59, s59, 1
	s_add_u32 s54, s54, s59
	s_addc_u32 s55, s55, 0
	s_add_u32 s54, s54, vcc_lo
	s_addc_u32 s55, s55, vcc_hi
	v_mul_u32_u24_e32 v28, s90, v29
	s_lshl_b32 s91, s91, 2
	global_load_dword v30, v26, s[50:51] nt
	s_add_u32 s50, s50, s91
	s_addc_u32 s51, s51, 0
	global_load_dword v31, v26, s[50:51] nt
	s_add_u32 s50, s50, s91
	s_addc_u32 s51, s51, 0
	global_load_dword v32, v26, s[50:51] nt
	s_add_u32 s50, s50, s91
	s_addc_u32 s51, s51, 0
	global_load_dword v33, v26, s[50:51] nt
	s_add_u32 s50, s50, s91
	s_addc_u32 s51, s51, 0
	global_load_dword v34, v26, s[50:51] nt
	s_add_u32 s50, s50, s91
	s_addc_u32 s51, s51, 0
	global_load_dword v35, v26, s[50:51] nt
	s_add_u32 s50, s50, s91
	s_addc_u32 s51, s51, 0
	global_load_dword v36, v26, s[50:51] nt
	s_add_u32 s50, s50, s91
	s_addc_u32 s51, s51, 0
	global_load_dword v37, v26, s[50:51] nt
	s_add_u32 s50, s50, s91
	s_addc_u32 s51, s51, 0
	global_load_dword v38, v26, s[50:51] nt
	s_add_u32 s50, s50, s91
	s_addc_u32 s51, s51, 0
	global_load_dword v39, v26, s[50:51] nt
	s_add_u32 s50, s50, s91
	s_addc_u32 s51, s51, 0
	global_load_dword v40, v26, s[50:51] nt
	s_add_u32 s50, s50, s91
	s_addc_u32 s51, s51, 0
	global_load_dword v41, v26, s[50:51] nt
	s_add_u32 s50, s50, s91
	s_addc_u32 s51, s51, 0
	global_load_dword v42, v26, s[50:51] nt
	s_add_u32 s50, s50, s91
	s_addc_u32 s51, s51, 0
	global_load_dword v43, v26, s[50:51] nt
	s_add_u32 s50, s50, s91
	s_addc_u32 s51, s51, 0
	global_load_dword v44, v26, s[50:51] nt
	s_add_u32 s50, s50, s91
	s_addc_u32 s51, s51, 0
	global_load_dword v45, v26, s[50:51] nt
	s_add_i32 s89, s89, s6
	s_cmpk_ge_i32 s89, 0x1680
	s_cbranch_scc1 .Lwf_pdrain2
	s_add_i32 s7, s89, 0xfffffe80
	s_mov_b32 s30, 2
	s_cmpk_ge_i32 s7, 0x300
	s_cselect_b32 s30, 3, s30
	s_cmpk_ge_i32 s7, 0x500
	s_cselect_b32 s30, 4, s30
	s_cmpk_ge_i32 s7, 0x700
	s_cselect_b32 s30, 5, s30
	s_cmpk_ge_i32 s7, 0x900
	s_cselect_b32 s30, 6, s30
	s_cmpk_ge_i32 s7, 0xb00
	s_cselect_b32 s30, 7, s30
	s_cmpk_ge_i32 s7, 0xd00
	s_cselect_b32 s30, 8, s30
	s_cmpk_ge_i32 s7, 0xf00
	s_cselect_b32 s30, 9, s30
	s_cmpk_ge_i32 s7, 0x1100
	s_cselect_b32 s30, 10, s30
	s_cmpk_ge_i32 s7, 0x1280
	s_cselect_b32 s30, 11, s30
	s_cmpk_ge_i32 s7, 0x1400
	s_cselect_b32 s30, 12, s30
	s_cmpk_ge_i32 s7, 0x1480
	s_cselect_b32 s30, 13, s30
	s_mul_i32 s59, s30, 48
	s_add_u32 s10, s0, s59
	s_addc_u32 s11, s1, 0
	s_load_dwordx2 s[50:51], s[10:11], 0x100
	s_load_dwordx2 s[56:57], s[10:11], 0x110
	s_load_dwordx2 s[90:91], s[10:11], 0x118
	s_load_dword s30, s[10:11], 0x128
	s_load_dwordx2 vcc, s[0:1], 0xf8
	s_waitcnt lgkmcnt(0)
	s_sub_i32 s7, s7, s30
	s_lshr_b32 s59, s90, 7
	s_add_i32 s10, s59, -1
	s_and_b32 s10, s7, s10
	s_ff1_i32_b32 s59, s59
	s_lshr_b32 s7, s7, s59
	s_lshl_b32 s10, s10, 7
	s_add_i32 s10, s10, s58
	s_lshl_b32 s11, s7, 6
	s_mul_i32 s59, s10, s91
	s_add_i32 s59, s59, s11
	s_lshl_b32 s59, s59, 2
	s_add_u32 s50, s50, s59
	s_addc_u32 s51, s51, 0
	s_mul_i32 s59, s11, s90
	s_add_i32 s59, s59, s10
	s_lshl_b32 s59, s59, 1
	s_add_u32 s56, s56, s59
	s_addc_u32 s57, s57, 0
	s_add_u32 s56, s56, vcc_lo
	s_addc_u32 s57, s57, vcc_hi
	v_mul_u32_u24_e32 v78, s90, v29
	s_lshl_b32 s91, s91, 2
	global_load_dword v46, v26, s[50:51] nt
	s_add_u32 s50, s50, s91
	s_addc_u32 s51, s51, 0
	global_load_dword v47, v26, s[50:51] nt
	s_add_u32 s50, s50, s91
	s_addc_u32 s51, s51, 0
	global_load_dword v48, v26, s[50:51] nt
	s_add_u32 s50, s50, s91
	s_addc_u32 s51, s51, 0
	global_load_dword v49, v26, s[50:51] nt
	s_add_u32 s50, s50, s91
	s_addc_u32 s51, s51, 0
	global_load_dword v50, v26, s[50:51] nt
	s_add_u32 s50, s50, s91
	s_addc_u32 s51, s51, 0
	global_load_dword v51, v26, s[50:51] nt
	s_add_u32 s50, s50, s91
	s_addc_u32 s51, s51, 0
	global_load_dword v52, v26, s[50:51] nt
	s_add_u32 s50, s50, s91
	s_addc_u32 s51, s51, 0
	global_load_dword v53, v26, s[50:51] nt
	s_add_u32 s50, s50, s91
	s_addc_u32 s51, s51, 0
	global_load_dword v54, v26, s[50:51] nt
	s_add_u32 s50, s50, s91
	s_addc_u32 s51, s51, 0
	global_load_dword v55, v26, s[50:51] nt
	s_add_u32 s50, s50, s91
	s_addc_u32 s51, s51, 0
	global_load_dword v56, v26, s[50:51] nt
	s_add_u32 s50, s50, s91
	s_addc_u32 s51, s51, 0
	global_load_dword v57, v26, s[50:51] nt
	s_add_u32 s50, s50, s91
	s_addc_u32 s51, s51, 0
	global_load_dword v58, v26, s[50:51] nt
	s_add_u32 s50, s50, s91
	s_addc_u32 s51, s51, 0
	global_load_dword v59, v26, s[50:51] nt
	s_add_u32 s50, s50, s91
	s_addc_u32 s51, s51, 0
	global_load_dword v60, v26, s[50:51] nt
	s_add_u32 s50, s50, s91
	s_addc_u32 s51, s51, 0
	global_load_dword v61, v26, s[50:51] nt
.Lwf_loop:
	s_waitcnt vmcnt(32)
	v_cvt_pk_bf16_f32 v0, v0, v1
	v_cvt_pk_bf16_f32 v1, v2, v3
	v_cvt_pk_bf16_f32 v2, v4, v5
	v_cvt_pk_bf16_f32 v3, v6, v7
	v_cvt_pk_bf16_f32 v4, v8, v9
	v_cvt_pk_bf16_f32 v5, v10, v11
	v_cvt_pk_bf16_f32 v6, v12, v13
	v_cvt_pk_bf16_f32 v7, v14, v15
	global_store_dwordx4 v27, v[0:3], s[52:53]
	global_store_dwordx4 v27, v[4:7], s[52:53] offset:16
	s_add_i32 s89, s89, s6
	s_cmpk_ge_i32 s89, 0x1680
	s_cbranch_scc1 .Lwf_drain0
	s_add_i32 s7, s89, 0xfffffe80
	s_mov_b32 s30, 2
	s_cmpk_ge_i32 s7, 0x300
	s_cselect_b32 s30, 3, s30
	s_cmpk_ge_i32 s7, 0x500
	s_cselect_b32 s30, 4, s30
	s_cmpk_ge_i32 s7, 0x700
	s_cselect_b32 s30, 5, s30
	s_cmpk_ge_i32 s7, 0x900
	s_cselect_b32 s30, 6, s30
	s_cmpk_ge_i32 s7, 0xb00
	s_cselect_b32 s30, 7, s30
	s_cmpk_ge_i32 s7, 0xd00
	s_cselect_b32 s30, 8, s30
	s_cmpk_ge_i32 s7, 0xf00
	s_cselect_b32 s30, 9, s30
	s_cmpk_ge_i32 s7, 0x1100
	s_cselect_b32 s30, 10, s30
	s_cmpk_ge_i32 s7, 0x1280
	s_cselect_b32 s30, 11, s30
	s_cmpk_ge_i32 s7, 0x1400
	s_cselect_b32 s30, 12, s30
	s_cmpk_ge_i32 s7, 0x1480
	s_cselect_b32 s30, 13, s30
	s_mul_i32 s59, s30, 48
	s_add_u32 s10, s0, s59
	s_addc_u32 s11, s1, 0
	s_load_dwordx2 s[50:51], s[10:11], 0x100
	s_load_dwordx2 s[52:53], s[10:11], 0x110
	s_load_dwordx2 s[90:91], s[10:11], 0x118
	s_load_dword s30, s[10:11], 0x128
	s_load_dwordx2 vcc, s[0:1], 0xf8
	s_waitcnt lgkmcnt(0)
	s_sub_i32 s7, s7, s30
	s_lshr_b32 s59, s90, 7
	s_add_i32 s10, s59, -1
	s_and_b32 s10, s7, s10
	s_ff1_i32_b32 s59, s59
	s_lshr_b32 s7, s7, s59
	s_lshl_b32 s10, s10, 7
	s_add_i32 s10, s10, s58
	s_lshl_b32 s11, s7, 6
	s_mul_i32 s59, s10, s91
	s_add_i32 s59, s59, s11
	s_lshl_b32 s59, s59, 2
	s_add_u32 s50, s50, s59
	s_addc_u32 s51, s51, 0
	s_mul_i32 s59, s11, s90
	s_add_i32 s59, s59, s10
	s_lshl_b32 s59, s59, 1
	s_add_u32 s52, s52, s59
	s_addc_u32 s53, s53, 0
	s_add_u32 s52, s52, vcc_lo
	s_addc_u32 s53, s53, vcc_hi
	v_mul_u32_u24_e32 v27, s90, v29
	s_lshl_b32 s91, s91, 2
	global_load_dword v0, v26, s[50:51] nt
	s_add_u32 s50, s50, s91
	s_addc_u32 s51, s51, 0
	global_load_dword v1, v26, s[50:51] nt
	s_add_u32 s50, s50, s91
	s_addc_u32 s51, s51, 0
	global_load_dword v2, v26, s[50:51] nt
	s_add_u32 s50, s50, s91
	s_addc_u32 s51, s51, 0
	global_load_dword v3, v26, s[50:51] nt
	s_add_u32 s50, s50, s91
	s_addc_u32 s51, s51, 0
	global_load_dword v4, v26, s[50:51] nt
	s_add_u32 s50, s50, s91
	s_addc_u32 s51, s51, 0
	global_load_dword v5, v26, s[50:51] nt
	s_add_u32 s50, s50, s91
	s_addc_u32 s51, s51, 0
	global_load_dword v6, v26, s[50:51] nt
	s_add_u32 s50, s50, s91
	s_addc_u32 s51, s51, 0
	global_load_dword v7, v26, s[50:51] nt
	s_add_u32 s50, s50, s91
	s_addc_u32 s51, s51, 0
	global_load_dword v8, v26, s[50:51] nt
	s_add_u32 s50, s50, s91
	s_addc_u32 s51, s51, 0
	global_load_dword v9, v26, s[50:51] nt
	s_add_u32 s50, s50, s91
	s_addc_u32 s51, s51, 0
	global_load_dword v10, v26, s[50:51] nt
	s_add_u32 s50, s50, s91
	s_addc_u32 s51, s51, 0
	global_load_dword v11, v26, s[50:51] nt
	s_add_u32 s50, s50, s91
	s_addc_u32 s51, s51, 0
	global_load_dword v12, v26, s[50:51] nt
	s_add_u32 s50, s50, s91
	s_addc_u32 s51, s51, 0
	global_load_dword v13, v26, s[50:51] nt
	s_add_u32 s50, s50, s91
	s_addc_u32 s51, s51, 0
	global_load_dword v14, v26, s[50:51] nt
	s_add_u32 s50, s50, s91
	s_addc_u32 s51, s51, 0
	global_load_dword v15, v26, s[50:51] nt
	s_waitcnt vmcnt(32)
	v_cvt_pk_bf16_f32 v30, v30, v31
	v_cvt_pk_bf16_f32 v31, v32, v33
	v_cvt_pk_bf16_f32 v32, v34, v35
	v_cvt_pk_bf16_f32 v33, v36, v37
	v_cvt_pk_bf16_f32 v34, v38, v39
	v_cvt_pk_bf16_f32 v35, v40, v41
	v_cvt_pk_bf16_f32 v36, v42, v43
	v_cvt_pk_bf16_f32 v37, v44, v45
	global_store_dwordx4 v28, v[30:33], s[54:55]
	global_store_dwordx4 v28, v[34:37], s[54:55] offset:16
	s_add_i32 s89, s89, s6
	s_cmpk_ge_i32 s89, 0x1680
	s_cbranch_scc1 .Lwf_drain1
	s_add_i32 s7, s89, 0xfffffe80
	s_mov_b32 s30, 2
	s_cmpk_ge_i32 s7, 0x300
	s_cselect_b32 s30, 3, s30
	s_cmpk_ge_i32 s7, 0x500
	s_cselect_b32 s30, 4, s30
	s_cmpk_ge_i32 s7, 0x700
	s_cselect_b32 s30, 5, s30
	s_cmpk_ge_i32 s7, 0x900
	s_cselect_b32 s30, 6, s30
	s_cmpk_ge_i32 s7, 0xb00
	s_cselect_b32 s30, 7, s30
	s_cmpk_ge_i32 s7, 0xd00
	s_cselect_b32 s30, 8, s30
	s_cmpk_ge_i32 s7, 0xf00
	s_cselect_b32 s30, 9, s30
	s_cmpk_ge_i32 s7, 0x1100
	s_cselect_b32 s30, 10, s30
	s_cmpk_ge_i32 s7, 0x1280
	s_cselect_b32 s30, 11, s30
	s_cmpk_ge_i32 s7, 0x1400
	s_cselect_b32 s30, 12, s30
	s_cmpk_ge_i32 s7, 0x1480
	s_cselect_b32 s30, 13, s30
	s_mul_i32 s59, s30, 48
	s_add_u32 s10, s0, s59
	s_addc_u32 s11, s1, 0
	s_load_dwordx2 s[50:51], s[10:11], 0x100
	s_load_dwordx2 s[54:55], s[10:11], 0x110
	s_load_dwordx2 s[90:91], s[10:11], 0x118
	s_load_dword s30, s[10:11], 0x128
	s_load_dwordx2 vcc, s[0:1], 0xf8
	s_waitcnt lgkmcnt(0)
	s_sub_i32 s7, s7, s30
	s_lshr_b32 s59, s90, 7
	s_add_i32 s10, s59, -1
	s_and_b32 s10, s7, s10
	s_ff1_i32_b32 s59, s59
	s_lshr_b32 s7, s7, s59
	s_lshl_b32 s10, s10, 7
	s_add_i32 s10, s10, s58
	s_lshl_b32 s11, s7, 6
	s_mul_i32 s59, s10, s91
	s_add_i32 s59, s59, s11
	s_lshl_b32 s59, s59, 2
	s_add_u32 s50, s50, s59
	s_addc_u32 s51, s51, 0
	s_mul_i32 s59, s11, s90
	s_add_i32 s59, s59, s10
	s_lshl_b32 s59, s59, 1
	s_add_u32 s54, s54, s59
	s_addc_u32 s55, s55, 0
	s_add_u32 s54, s54, vcc_lo
	s_addc_u32 s55, s55, vcc_hi
	v_mul_u32_u24_e32 v28, s90, v29
	s_lshl_b32 s91, s91, 2
	global_load_dword v30, v26, s[50:51] nt
	s_add_u32 s50, s50, s91
	s_addc_u32 s51, s51, 0
	global_load_dword v31, v26, s[50:51] nt
	s_add_u32 s50, s50, s91
	s_addc_u32 s51, s51, 0
	global_load_dword v32, v26, s[50:51] nt
	s_add_u32 s50, s50, s91
	s_addc_u32 s51, s51, 0
	global_load_dword v33, v26, s[50:51] nt
	s_add_u32 s50, s50, s91
	s_addc_u32 s51, s51, 0
	global_load_dword v34, v26, s[50:51] nt
	s_add_u32 s50, s50, s91
	s_addc_u32 s51, s51, 0
	global_load_dword v35, v26, s[50:51] nt
	s_add_u32 s50, s50, s91
	s_addc_u32 s51, s51, 0
	global_load_dword v36, v26, s[50:51] nt
	s_add_u32 s50, s50, s91
	s_addc_u32 s51, s51, 0
	global_load_dword v37, v26, s[50:51] nt
	s_add_u32 s50, s50, s91
	s_addc_u32 s51, s51, 0
	global_load_dword v38, v26, s[50:51] nt
	s_add_u32 s50, s50, s91
	s_addc_u32 s51, s51, 0
	global_load_dword v39, v26, s[50:51] nt
	s_add_u32 s50, s50, s91
	s_addc_u32 s51, s51, 0
	global_load_dword v40, v26, s[50:51] nt
	s_add_u32 s50, s50, s91
	s_addc_u32 s51, s51, 0
	global_load_dword v41, v26, s[50:51] nt
	s_add_u32 s50, s50, s91
	s_addc_u32 s51, s51, 0
	global_load_dword v42, v26, s[50:51] nt
	s_add_u32 s50, s50, s91
	s_addc_u32 s51, s51, 0
	global_load_dword v43, v26, s[50:51] nt
	s_add_u32 s50, s50, s91
	s_addc_u32 s51, s51, 0
	global_load_dword v44, v26, s[50:51] nt
	s_add_u32 s50, s50, s91
	s_addc_u32 s51, s51, 0
	global_load_dword v45, v26, s[50:51] nt
	s_waitcnt vmcnt(32)
	v_cvt_pk_bf16_f32 v46, v46, v47
	v_cvt_pk_bf16_f32 v47, v48, v49
	v_cvt_pk_bf16_f32 v48, v50, v51
	v_cvt_pk_bf16_f32 v49, v52, v53
	v_cvt_pk_bf16_f32 v50, v54, v55
	v_cvt_pk_bf16_f32 v51, v56, v57
	v_cvt_pk_bf16_f32 v52, v58, v59
	v_cvt_pk_bf16_f32 v53, v60, v61
	global_store_dwordx4 v78, v[46:49], s[56:57]
	global_store_dwordx4 v78, v[50:53], s[56:57] offset:16
	s_add_i32 s89, s89, s6
	s_cmpk_ge_i32 s89, 0x1680
	s_cbranch_scc1 .Lwf_drain2
	s_add_i32 s7, s89, 0xfffffe80
	s_mov_b32 s30, 2
	s_cmpk_ge_i32 s7, 0x300
	s_cselect_b32 s30, 3, s30
	s_cmpk_ge_i32 s7, 0x500
	s_cselect_b32 s30, 4, s30
	s_cmpk_ge_i32 s7, 0x700
	s_cselect_b32 s30, 5, s30
	s_cmpk_ge_i32 s7, 0x900
	s_cselect_b32 s30, 6, s30
	s_cmpk_ge_i32 s7, 0xb00
	s_cselect_b32 s30, 7, s30
	s_cmpk_ge_i32 s7, 0xd00
	s_cselect_b32 s30, 8, s30
	s_cmpk_ge_i32 s7, 0xf00
	s_cselect_b32 s30, 9, s30
	s_cmpk_ge_i32 s7, 0x1100
	s_cselect_b32 s30, 10, s30
	s_cmpk_ge_i32 s7, 0x1280
	s_cselect_b32 s30, 11, s30
	s_cmpk_ge_i32 s7, 0x1400
	s_cselect_b32 s30, 12, s30
	s_cmpk_ge_i32 s7, 0x1480
	s_cselect_b32 s30, 13, s30
	s_mul_i32 s59, s30, 48
	s_add_u32 s10, s0, s59
	s_addc_u32 s11, s1, 0
	s_load_dwordx2 s[50:51], s[10:11], 0x100
	s_load_dwordx2 s[56:57], s[10:11], 0x110
	s_load_dwordx2 s[90:91], s[10:11], 0x118
	s_load_dword s30, s[10:11], 0x128
	s_load_dwordx2 vcc, s[0:1], 0xf8
	s_waitcnt lgkmcnt(0)
	s_sub_i32 s7, s7, s30
	s_lshr_b32 s59, s90, 7
	s_add_i32 s10, s59, -1
	s_and_b32 s10, s7, s10
	s_ff1_i32_b32 s59, s59
	s_lshr_b32 s7, s7, s59
	s_lshl_b32 s10, s10, 7
	s_add_i32 s10, s10, s58
	s_lshl_b32 s11, s7, 6
	s_mul_i32 s59, s10, s91
	s_add_i32 s59, s59, s11
	s_lshl_b32 s59, s59, 2
	s_add_u32 s50, s50, s59
	s_addc_u32 s51, s51, 0
	s_mul_i32 s59, s11, s90
	s_add_i32 s59, s59, s10
	s_lshl_b32 s59, s59, 1
	s_add_u32 s56, s56, s59
	s_addc_u32 s57, s57, 0
	s_add_u32 s56, s56, vcc_lo
	s_addc_u32 s57, s57, vcc_hi
	v_mul_u32_u24_e32 v78, s90, v29
	s_lshl_b32 s91, s91, 2
	global_load_dword v46, v26, s[50:51] nt
	s_add_u32 s50, s50, s91
	s_addc_u32 s51, s51, 0
	global_load_dword v47, v26, s[50:51] nt
	s_add_u32 s50, s50, s91
	s_addc_u32 s51, s51, 0
	global_load_dword v48, v26, s[50:51] nt
	s_add_u32 s50, s50, s91
	s_addc_u32 s51, s51, 0
	global_load_dword v49, v26, s[50:51] nt
	s_add_u32 s50, s50, s91
	s_addc_u32 s51, s51, 0
	global_load_dword v50, v26, s[50:51] nt
	s_add_u32 s50, s50, s91
	s_addc_u32 s51, s51, 0
	global_load_dword v51, v26, s[50:51] nt
	s_add_u32 s50, s50, s91
	s_addc_u32 s51, s51, 0
	global_load_dword v52, v26, s[50:51] nt
	s_add_u32 s50, s50, s91
	s_addc_u32 s51, s51, 0
	global_load_dword v53, v26, s[50:51] nt
	s_add_u32 s50, s50, s91
	s_addc_u32 s51, s51, 0
	global_load_dword v54, v26, s[50:51] nt
	s_add_u32 s50, s50, s91
	s_addc_u32 s51, s51, 0
	global_load_dword v55, v26, s[50:51] nt
	s_add_u32 s50, s50, s91
	s_addc_u32 s51, s51, 0
	global_load_dword v56, v26, s[50:51] nt
	s_add_u32 s50, s50, s91
	s_addc_u32 s51, s51, 0
	global_load_dword v57, v26, s[50:51] nt
	s_add_u32 s50, s50, s91
	s_addc_u32 s51, s51, 0
	global_load_dword v58, v26, s[50:51] nt
	s_add_u32 s50, s50, s91
	s_addc_u32 s51, s51, 0
	global_load_dword v59, v26, s[50:51] nt
	s_add_u32 s50, s50, s91
	s_addc_u32 s51, s51, 0
	global_load_dword v60, v26, s[50:51] nt
	s_add_u32 s50, s50, s91
	s_addc_u32 s51, s51, 0
	global_load_dword v61, v26, s[50:51] nt
	s_branch .Lwf_loop
.Lwf_drain0:
	s_waitcnt vmcnt(0)
	v_cvt_pk_bf16_f32 v30, v30, v31
	v_cvt_pk_bf16_f32 v31, v32, v33
	v_cvt_pk_bf16_f32 v32, v34, v35
	v_cvt_pk_bf16_f32 v33, v36, v37
	v_cvt_pk_bf16_f32 v34, v38, v39
	v_cvt_pk_bf16_f32 v35, v40, v41
	v_cvt_pk_bf16_f32 v36, v42, v43
	v_cvt_pk_bf16_f32 v37, v44, v45
	global_store_dwordx4 v28, v[30:33], s[54:55]
	global_store_dwordx4 v28, v[34:37], s[54:55] offset:16
	v_cvt_pk_bf16_f32 v46, v46, v47
	v_cvt_pk_bf16_f32 v47, v48, v49
	v_cvt_pk_bf16_f32 v48, v50, v51
	v_cvt_pk_bf16_f32 v49, v52, v53
	v_cvt_pk_bf16_f32 v50, v54, v55
	v_cvt_pk_bf16_f32 v51, v56, v57
	v_cvt_pk_bf16_f32 v52, v58, v59
	v_cvt_pk_bf16_f32 v53, v60, v61
	global_store_dwordx4 v78, v[46:49], s[56:57]
	global_store_dwordx4 v78, v[50:53], s[56:57] offset:16
	s_branch .Lwf_done
.Lwf_drain1:
	s_waitcnt vmcnt(0)
	v_cvt_pk_bf16_f32 v46, v46, v47
	v_cvt_pk_bf16_f32 v47, v48, v49
	v_cvt_pk_bf16_f32 v48, v50, v51
	v_cvt_pk_bf16_f32 v49, v52, v53
	v_cvt_pk_bf16_f32 v50, v54, v55
	v_cvt_pk_bf16_f32 v51, v56, v57
	v_cvt_pk_bf16_f32 v52, v58, v59
	v_cvt_pk_bf16_f32 v53, v60, v61
	global_store_dwordx4 v78, v[46:49], s[56:57]
	global_store_dwordx4 v78, v[50:53], s[56:57] offset:16
	v_cvt_pk_bf16_f32 v0, v0, v1
	v_cvt_pk_bf16_f32 v1, v2, v3
	v_cvt_pk_bf16_f32 v2, v4, v5
	v_cvt_pk_bf16_f32 v3, v6, v7
	v_cvt_pk_bf16_f32 v4, v8, v9
	v_cvt_pk_bf16_f32 v5, v10, v11
	v_cvt_pk_bf16_f32 v6, v12, v13
	v_cvt_pk_bf16_f32 v7, v14, v15
	global_store_dwordx4 v27, v[0:3], s[52:53]
	global_store_dwordx4 v27, v[4:7], s[52:53] offset:16
	s_branch .Lwf_done
.Lwf_drain2:
	s_waitcnt vmcnt(0)
	v_cvt_pk_bf16_f32 v0, v0, v1
	v_cvt_pk_bf16_f32 v1, v2, v3
	v_cvt_pk_bf16_f32 v2, v4, v5
	v_cvt_pk_bf16_f32 v3, v6, v7
	v_cvt_pk_bf16_f32 v4, v8, v9
	v_cvt_pk_bf16_f32 v5, v10, v11
	v_cvt_pk_bf16_f32 v6, v12, v13
	v_cvt_pk_bf16_f32 v7, v14, v15
	global_store_dwordx4 v27, v[0:3], s[52:53]
	global_store_dwordx4 v27, v[4:7], s[52:53] offset:16
	v_cvt_pk_bf16_f32 v30, v30, v31
	v_cvt_pk_bf16_f32 v31, v32, v33
	v_cvt_pk_bf16_f32 v32, v34, v35
	v_cvt_pk_bf16_f32 v33, v36, v37
	v_cvt_pk_bf16_f32 v34, v38, v39
	v_cvt_pk_bf16_f32 v35, v40, v41
	v_cvt_pk_bf16_f32 v36, v42, v43
	v_cvt_pk_bf16_f32 v37, v44, v45
	global_store_dwordx4 v28, v[30:33], s[54:55]
	global_store_dwordx4 v28, v[34:37], s[54:55] offset:16
	s_branch .Lwf_done
.Lwf_pdrain1:
	s_waitcnt vmcnt(0)
	v_cvt_pk_bf16_f32 v0, v0, v1
	v_cvt_pk_bf16_f32 v1, v2, v3
	v_cvt_pk_bf16_f32 v2, v4, v5
	v_cvt_pk_bf16_f32 v3, v6, v7
	v_cvt_pk_bf16_f32 v4, v8, v9
	v_cvt_pk_bf16_f32 v5, v10, v11
	v_cvt_pk_bf16_f32 v6, v12, v13
	v_cvt_pk_bf16_f32 v7, v14, v15
	global_store_dwordx4 v27, v[0:3], s[52:53]
	global_store_dwordx4 v27, v[4:7], s[52:53] offset:16
	s_branch .Lwf_done
.Lwf_pdrain2:
	s_waitcnt vmcnt(0)
	v_cvt_pk_bf16_f32 v0, v0, v1
	v_cvt_pk_bf16_f32 v1, v2, v3
	v_cvt_pk_bf16_f32 v2, v4, v5
	v_cvt_pk_bf16_f32 v3, v6, v7
	v_cvt_pk_bf16_f32 v4, v8, v9
	v_cvt_pk_bf16_f32 v5, v10, v11
	v_cvt_pk_bf16_f32 v6, v12, v13
	v_cvt_pk_bf16_f32 v7, v14, v15
	global_store_dwordx4 v27, v[0:3], s[52:53]
	global_store_dwordx4 v27, v[4:7], s[52:53] offset:16
	v_cvt_pk_bf16_f32 v30, v30, v31
	v_cvt_pk_bf16_f32 v31, v32, v33
	v_cvt_pk_bf16_f32 v32, v34, v35
	v_cvt_pk_bf16_f32 v33, v36, v37
	v_cvt_pk_bf16_f32 v34, v38, v39
	v_cvt_pk_bf16_f32 v35, v40, v41
	v_cvt_pk_bf16_f32 v36, v42, v43
	v_cvt_pk_bf16_f32 v37, v44, v45
	global_store_dwordx4 v28, v[30:33], s[54:55]
	global_store_dwordx4 v28, v[34:37], s[54:55] offset:16
.Lwf_done:
	s_cmp_ge_i32 s89, s62
	s_cbranch_scc1 .LBB0_113
